# P0 x-row conversion loop: the 16 loads of each unrolled iteration hoisted to its top with counted vmcnt waits (was: 2 loads, vmcnt(0), compute, store per step)
# baseline (speedup 1.0000x reference)
.LBB0_114:
	v_lshl_add_u64 v[52:53], v[48:49], 0, s[4:5]
	global_load_dwordx4 v[124:127], v[52:53], off nt
	global_load_dwordx4 v[128:131], v[52:53], off offset:16 nt
	global_load_dwordx4 v[132:135], v[52:53], off offset:128 nt
	global_load_dwordx4 v[136:139], v[52:53], off offset:144 nt
	global_load_dwordx4 v[140:143], v[52:53], off offset:256 nt
	global_load_dwordx4 v[144:147], v[52:53], off offset:272 nt
	global_load_dwordx4 v[148:151], v[52:53], off offset:384 nt
	global_load_dwordx4 v[152:155], v[52:53], off offset:400 nt
	global_load_dwordx4 v[156:159], v[52:53], off offset:512 nt
	global_load_dwordx4 v[170:173], v[52:53], off offset:528 nt
	global_load_dwordx4 v[174:177], v[52:53], off offset:640 nt
	global_load_dwordx4 v[178:181], v[52:53], off offset:656 nt
	global_load_dwordx4 v[182:185], v[52:53], off offset:768 nt
	global_load_dwordx4 v[186:189], v[52:53], off offset:784 nt
	global_load_dwordx4 v[190:193], v[52:53], off offset:896 nt
	global_load_dwordx4 v[194:197], v[52:53], off offset:912 nt
	ds_read_b128 v[20:23], v47
	ds_read_b128 v[4:7], v47 offset:64
	ds_read_b128 v[8:11], v47 offset:128
	ds_read_b128 v[12:15], v47 offset:192
	ds_read_b128 v[16:19], v47 offset:256
	ds_read_b128 v[24:27], v47 offset:320
	ds_read_b128 v[28:31], v47 offset:384
	ds_read_b128 v[32:35], v47 offset:448
	v_add_co_u32_e32 v54, vcc, s20, v50
	s_add_u32 s4, s4, 0x400
	s_nop 0
	v_addc_co_u32_e32 v55, vcc, -1, v51, vcc
	s_addc_u32 s5, s5, 0
	v_add_u32_e32 v47, 0x200, v47
	s_cmpk_eq_i32 s4, 0x2000
	s_waitcnt vmcnt(15)
	v_mov_b32_e32 v80, v125
	s_waitcnt vmcnt(14)
	v_mov_b32_e32 v81, v129
	v_mov_b32_e32 v84, v127
	v_mov_b32_e32 v85, v131
	v_and_b32_sdwa v88, v127, v67 dst_sel:DWORD dst_unused:UNUSED_PAD src0_sel:WORD_1 src1_sel:DWORD
	v_and_b32_sdwa v89, v125, v67 dst_sel:DWORD dst_unused:UNUSED_PAD src0_sel:WORD_1 src1_sel:DWORD
	v_and_b32_sdwa v91, v128, v67 dst_sel:DWORD dst_unused:UNUSED_PAD src0_sel:WORD_1 src1_sel:DWORD
	v_and_b32_sdwa v92, v131, v67 dst_sel:DWORD dst_unused:UNUSED_PAD src0_sel:WORD_1 src1_sel:DWORD
	v_and_b32_sdwa v93, v129, v67 dst_sel:DWORD dst_unused:UNUSED_PAD src0_sel:WORD_1 src1_sel:DWORD
	v_mov_b32_e32 v78, v124
	v_mov_b32_e32 v79, v128
	v_mov_b32_e32 v82, v126
	v_mov_b32_e32 v83, v130
	v_and_b32_sdwa v86, v126, v67 dst_sel:DWORD dst_unused:UNUSED_PAD src0_sel:WORD_1 src1_sel:DWORD
	v_and_b32_sdwa v87, v124, v67 dst_sel:DWORD dst_unused:UNUSED_PAD src0_sel:WORD_1 src1_sel:DWORD
	v_and_b32_sdwa v90, v130, v67 dst_sel:DWORD dst_unused:UNUSED_PAD src0_sel:WORD_1 src1_sel:DWORD
	v_pk_mul_f32 v[80:81], v[80:81], v[80:81]
	v_pk_mul_f32 v[84:85], v[84:85], v[84:85]
	v_add3_u32 v88, v127, v88, s9
	v_add3_u32 v89, v125, v89, s9
	v_add3_u32 v91, v128, v91, s9
	v_add3_u32 v74, v131, v92, s9
	v_add3_u32 v75, v129, v93, s9
	v_add3_u32 v87, v124, v87, s9
	v_add3_u32 v86, v126, v86, s9
	v_add3_u32 v76, v130, v90, s9
	v_pk_fma_f32 v[70:71], v[78:79], v[78:79], v[80:81]
	v_pk_fma_f32 v[72:73], v[82:83], v[82:83], v[84:85]
	v_and_b32_e32 v77, 0xffff0000, v88
	v_and_b32_e32 v78, 0xffff0000, v89
	v_and_b32_e32 v79, 0xffff0000, v74
	v_and_b32_e32 v80, 0xffff0000, v75
	v_pk_add_f32 v[74:75], v[70:71], v[72:73]
	v_or_b32_sdwa v71, v77, v86 dst_sel:DWORD dst_unused:UNUSED_PAD src0_sel:DWORD src1_sel:WORD_1
	v_or_b32_sdwa v70, v78, v87 dst_sel:DWORD dst_unused:UNUSED_PAD src0_sel:DWORD src1_sel:WORD_1
	v_or_b32_sdwa v73, v79, v76 dst_sel:DWORD dst_unused:UNUSED_PAD src0_sel:DWORD src1_sel:WORD_1
	v_or_b32_sdwa v72, v80, v91 dst_sel:DWORD dst_unused:UNUSED_PAD src0_sel:DWORD src1_sel:WORD_1
	global_store_dwordx4 v[54:55], v[70:73], off offset:-3072
	v_add_f32_e32 v82, v74, v75
	v_add_f32_e32 v69, v69, v82
	s_waitcnt lgkmcnt(7)
	v_mfma_f32_16x16x32_bf16 v[0:3], v[70:73], v[20:23], v[0:3]
	s_waitcnt vmcnt(14)
	v_mov_b32_e32 v20, v133
	s_waitcnt vmcnt(13)
	v_mov_b32_e32 v21, v137
	v_and_b32_sdwa v22, v134, v67 dst_sel:DWORD dst_unused:UNUSED_PAD src0_sel:WORD_1 src1_sel:DWORD
	v_and_b32_sdwa v23, v132, v67 dst_sel:DWORD dst_unused:UNUSED_PAD src0_sel:WORD_1 src1_sel:DWORD
	v_and_b32_sdwa v70, v135, v67 dst_sel:DWORD dst_unused:UNUSED_PAD src0_sel:WORD_1 src1_sel:DWORD
	v_and_b32_sdwa v71, v133, v67 dst_sel:DWORD dst_unused:UNUSED_PAD src0_sel:WORD_1 src1_sel:DWORD
	v_and_b32_sdwa v72, v138, v67 dst_sel:DWORD dst_unused:UNUSED_PAD src0_sel:WORD_1 src1_sel:DWORD
	v_and_b32_sdwa v73, v136, v67 dst_sel:DWORD dst_unused:UNUSED_PAD src0_sel:WORD_1 src1_sel:DWORD
	v_and_b32_sdwa v82, v139, v67 dst_sel:DWORD dst_unused:UNUSED_PAD src0_sel:WORD_1 src1_sel:DWORD
	v_and_b32_sdwa v83, v137, v67 dst_sel:DWORD dst_unused:UNUSED_PAD src0_sel:WORD_1 src1_sel:DWORD
	v_pk_mul_f32 v[120:121], v[20:21], v[20:21]
	v_add3_u32 v20, v132, v23, s9
	v_add3_u32 v21, v134, v22, s9
	v_add3_u32 v22, v135, v70, s9
	v_add3_u32 v23, v133, v71, s9
	v_add3_u32 v70, v136, v73, s9
	v_add3_u32 v71, v138, v72, s9
	v_add3_u32 v72, v139, v82, s9
	v_add3_u32 v73, v137, v83, s9
	v_and_b32_e32 v22, 0xffff0000, v22
	v_and_b32_e32 v23, 0xffff0000, v23
	v_and_b32_e32 v72, 0xffff0000, v72
	v_and_b32_e32 v73, 0xffff0000, v73
	v_or_b32_sdwa v21, v22, v21 dst_sel:DWORD dst_unused:UNUSED_PAD src0_sel:DWORD src1_sel:WORD_1
	v_or_b32_sdwa v20, v23, v20 dst_sel:DWORD dst_unused:UNUSED_PAD src0_sel:DWORD src1_sel:WORD_1
	v_or_b32_sdwa v23, v72, v71 dst_sel:DWORD dst_unused:UNUSED_PAD src0_sel:DWORD src1_sel:WORD_1
	v_or_b32_sdwa v22, v73, v70 dst_sel:DWORD dst_unused:UNUSED_PAD src0_sel:DWORD src1_sel:WORD_1
	global_store_dwordx4 v[54:55], v[20:23], off offset:-2048
	v_mov_b32_e32 v114, v132
	v_mov_b32_e32 v116, v134
	v_mov_b32_e32 v118, v135
	v_mov_b32_e32 v117, v138
	v_mov_b32_e32 v119, v139
	v_mov_b32_e32 v115, v136
	v_pk_fma_f32 v[114:115], v[114:115], v[114:115], v[120:121]
	s_waitcnt lgkmcnt(6)
	v_mfma_f32_16x16x32_bf16 v[0:3], v[20:23], v[4:7], v[0:3]
	s_waitcnt vmcnt(13)
	v_and_b32_sdwa v79, v140, v67 dst_sel:DWORD dst_unused:UNUSED_PAD src0_sel:WORD_1 src1_sel:DWORD
	v_and_b32_sdwa v80, v143, v67 dst_sel:DWORD dst_unused:UNUSED_PAD src0_sel:WORD_1 src1_sel:DWORD
	v_and_b32_sdwa v81, v141, v67 dst_sel:DWORD dst_unused:UNUSED_PAD src0_sel:WORD_1 src1_sel:DWORD
	s_waitcnt vmcnt(12)
	v_and_b32_sdwa v82, v146, v67 dst_sel:DWORD dst_unused:UNUSED_PAD src0_sel:WORD_1 src1_sel:DWORD
	v_and_b32_sdwa v84, v147, v67 dst_sel:DWORD dst_unused:UNUSED_PAD src0_sel:WORD_1 src1_sel:DWORD
	v_and_b32_sdwa v85, v145, v67 dst_sel:DWORD dst_unused:UNUSED_PAD src0_sel:WORD_1 src1_sel:DWORD
	v_and_b32_sdwa v78, v142, v67 dst_sel:DWORD dst_unused:UNUSED_PAD src0_sel:WORD_1 src1_sel:DWORD
	v_and_b32_sdwa v83, v144, v67 dst_sel:DWORD dst_unused:UNUSED_PAD src0_sel:WORD_1 src1_sel:DWORD
	v_add3_u32 v86, v140, v79, s9
	v_add3_u32 v79, v143, v80, s9
	v_add3_u32 v80, v141, v81, s9
	v_add3_u32 v81, v146, v82, s9
	v_add3_u32 v82, v147, v84, s9
	v_add3_u32 v84, v145, v85, s9
	v_add3_u32 v78, v142, v78, s9
	v_add3_u32 v83, v144, v83, s9
	v_and_b32_e32 v79, 0xffff0000, v79
	v_and_b32_e32 v80, 0xffff0000, v80
	v_and_b32_e32 v82, 0xffff0000, v82
	v_and_b32_e32 v84, 0xffff0000, v84
	v_or_b32_sdwa v79, v79, v78 dst_sel:DWORD dst_unused:UNUSED_PAD src0_sel:DWORD src1_sel:WORD_1
	v_or_b32_sdwa v78, v80, v86 dst_sel:DWORD dst_unused:UNUSED_PAD src0_sel:DWORD src1_sel:WORD_1
	v_or_b32_sdwa v81, v82, v81 dst_sel:DWORD dst_unused:UNUSED_PAD src0_sel:DWORD src1_sel:WORD_1
	v_or_b32_sdwa v80, v84, v83 dst_sel:DWORD dst_unused:UNUSED_PAD src0_sel:DWORD src1_sel:WORD_1
	global_store_dwordx4 v[54:55], v[78:81], off offset:-1024
	s_waitcnt lgkmcnt(5)
	v_mfma_f32_16x16x32_bf16 v[0:3], v[78:81], v[8:11], v[0:3]
	s_waitcnt vmcnt(12)
	v_and_b32_sdwa v90, v151, v67 dst_sel:DWORD dst_unused:UNUSED_PAD src0_sel:WORD_1 src1_sel:DWORD
	v_and_b32_sdwa v91, v149, v67 dst_sel:DWORD dst_unused:UNUSED_PAD src0_sel:WORD_1 src1_sel:DWORD
	s_waitcnt vmcnt(11)
	v_and_b32_sdwa v93, v152, v67 dst_sel:DWORD dst_unused:UNUSED_PAD src0_sel:WORD_1 src1_sel:DWORD
	v_and_b32_sdwa v94, v155, v67 dst_sel:DWORD dst_unused:UNUSED_PAD src0_sel:WORD_1 src1_sel:DWORD
	v_and_b32_sdwa v95, v153, v67 dst_sel:DWORD dst_unused:UNUSED_PAD src0_sel:WORD_1 src1_sel:DWORD
	v_and_b32_sdwa v54, v150, v67 dst_sel:DWORD dst_unused:UNUSED_PAD src0_sel:WORD_1 src1_sel:DWORD
	v_and_b32_sdwa v55, v148, v67 dst_sel:DWORD dst_unused:UNUSED_PAD src0_sel:WORD_1 src1_sel:DWORD
	v_and_b32_sdwa v92, v154, v67 dst_sel:DWORD dst_unused:UNUSED_PAD src0_sel:WORD_1 src1_sel:DWORD
	v_add3_u32 v90, v151, v90, s9
	v_add3_u32 v91, v149, v91, s9
	v_add3_u32 v96, v152, v93, s9
	v_add3_u32 v93, v155, v94, s9
	v_add3_u32 v94, v153, v95, s9
	v_add3_u32 v55, v148, v55, s9
	v_add3_u32 v54, v150, v54, s9
	v_add3_u32 v92, v154, v92, s9
	v_and_b32_e32 v90, 0xffff0000, v90
	v_and_b32_e32 v95, 0xffff0000, v91
	v_and_b32_e32 v93, 0xffff0000, v93
	v_and_b32_e32 v94, 0xffff0000, v94
	v_or_b32_sdwa v91, v90, v54 dst_sel:DWORD dst_unused:UNUSED_PAD src0_sel:DWORD src1_sel:WORD_1
	v_or_b32_sdwa v90, v95, v55 dst_sel:DWORD dst_unused:UNUSED_PAD src0_sel:DWORD src1_sel:WORD_1
	v_or_b32_sdwa v93, v93, v92 dst_sel:DWORD dst_unused:UNUSED_PAD src0_sel:DWORD src1_sel:WORD_1
	v_or_b32_sdwa v92, v94, v96 dst_sel:DWORD dst_unused:UNUSED_PAD src0_sel:DWORD src1_sel:WORD_1
	global_store_dwordx4 v[50:51], v[90:93], off offset:-4096
	v_mov_b32_e32 v10, v149
	v_mov_b32_e32 v11, v153
	v_mov_b32_e32 v8, v148
	v_mov_b32_e32 v9, v152
	v_pk_mul_f32 v[10:11], v[10:11], v[10:11]
	s_waitcnt lgkmcnt(4)
	v_mfma_f32_16x16x32_bf16 v[0:3], v[90:93], v[12:15], v[0:3]
	v_fma_f32 v8, v8, v8, v10
	v_fma_f32 v9, v9, v9, v11
	s_waitcnt vmcnt(11)
	v_and_b32_sdwa v102, v159, v67 dst_sel:DWORD dst_unused:UNUSED_PAD src0_sel:WORD_1 src1_sel:DWORD
	v_and_b32_sdwa v103, v157, v67 dst_sel:DWORD dst_unused:UNUSED_PAD src0_sel:WORD_1 src1_sel:DWORD
	s_waitcnt vmcnt(10)
	v_and_b32_sdwa v105, v170, v67 dst_sel:DWORD dst_unused:UNUSED_PAD src0_sel:WORD_1 src1_sel:DWORD
	v_and_b32_sdwa v106, v173, v67 dst_sel:DWORD dst_unused:UNUSED_PAD src0_sel:WORD_1 src1_sel:DWORD
	v_and_b32_sdwa v107, v171, v67 dst_sel:DWORD dst_unused:UNUSED_PAD src0_sel:WORD_1 src1_sel:DWORD
	v_and_b32_sdwa v54, v158, v67 dst_sel:DWORD dst_unused:UNUSED_PAD src0_sel:WORD_1 src1_sel:DWORD
	v_and_b32_sdwa v55, v156, v67 dst_sel:DWORD dst_unused:UNUSED_PAD src0_sel:WORD_1 src1_sel:DWORD
	v_and_b32_sdwa v104, v172, v67 dst_sel:DWORD dst_unused:UNUSED_PAD src0_sel:WORD_1 src1_sel:DWORD
	v_add3_u32 v102, v159, v102, s9
	v_add3_u32 v103, v157, v103, s9
	v_add3_u32 v108, v170, v105, s9
	v_add3_u32 v105, v173, v106, s9
	v_add3_u32 v106, v171, v107, s9
	v_add3_u32 v55, v156, v55, s9
	v_add3_u32 v54, v158, v54, s9
	v_add3_u32 v104, v172, v104, s9
	v_and_b32_e32 v102, 0xffff0000, v102
	v_and_b32_e32 v107, 0xffff0000, v103
	v_and_b32_e32 v105, 0xffff0000, v105
	v_and_b32_e32 v106, 0xffff0000, v106
	v_or_b32_sdwa v103, v102, v54 dst_sel:DWORD dst_unused:UNUSED_PAD src0_sel:DWORD src1_sel:WORD_1
	v_or_b32_sdwa v102, v107, v55 dst_sel:DWORD dst_unused:UNUSED_PAD src0_sel:DWORD src1_sel:WORD_1
	v_or_b32_sdwa v105, v105, v104 dst_sel:DWORD dst_unused:UNUSED_PAD src0_sel:DWORD src1_sel:WORD_1
	v_or_b32_sdwa v104, v106, v108 dst_sel:DWORD dst_unused:UNUSED_PAD src0_sel:DWORD src1_sel:WORD_1
	global_store_dwordx4 v[50:51], v[102:105], off offset:-3072
	v_pk_mul_f32 v[54:55], v[118:119], v[118:119]
	v_mov_b32_e32 v14, v157
	v_pk_fma_f32 v[54:55], v[116:117], v[116:117], v[54:55]
	v_mov_b32_e32 v15, v171
	v_pk_add_f32 v[54:55], v[114:115], v[54:55]
	v_mov_b32_e32 v12, v156
	v_add_f32_e32 v54, v54, v55
	v_add_f32_e32 v69, v69, v54
	v_mov_b32_e32 v54, v140
	v_mov_b32_e32 v55, v144
	v_mov_b32_e32 v74, v142
	v_mov_b32_e32 v72, v143
	v_mov_b32_e32 v73, v147
	v_pk_mul_f32 v[72:73], v[72:73], v[72:73]
	v_mov_b32_e32 v13, v170
	v_pk_mul_f32 v[14:15], v[14:15], v[14:15]
	s_waitcnt lgkmcnt(3)
	v_mfma_f32_16x16x32_bf16 v[0:3], v[102:105], v[16:19], v[0:3]
	v_fma_f32 v12, v12, v12, v14
	v_fma_f32 v13, v13, v13, v15
	s_waitcnt vmcnt(10)
	v_and_b32_sdwa v5, v174, v67 dst_sel:DWORD dst_unused:UNUSED_PAD src0_sel:WORD_1 src1_sel:DWORD
	v_and_b32_sdwa v6, v177, v67 dst_sel:DWORD dst_unused:UNUSED_PAD src0_sel:WORD_1 src1_sel:DWORD
	v_and_b32_sdwa v7, v175, v67 dst_sel:DWORD dst_unused:UNUSED_PAD src0_sel:WORD_1 src1_sel:DWORD
	s_waitcnt vmcnt(9)
	v_and_b32_sdwa v20, v180, v67 dst_sel:DWORD dst_unused:UNUSED_PAD src0_sel:WORD_1 src1_sel:DWORD
	v_and_b32_sdwa v22, v181, v67 dst_sel:DWORD dst_unused:UNUSED_PAD src0_sel:WORD_1 src1_sel:DWORD
	v_and_b32_sdwa v23, v179, v67 dst_sel:DWORD dst_unused:UNUSED_PAD src0_sel:WORD_1 src1_sel:DWORD
	v_and_b32_sdwa v4, v176, v67 dst_sel:DWORD dst_unused:UNUSED_PAD src0_sel:WORD_1 src1_sel:DWORD
	v_and_b32_sdwa v21, v178, v67 dst_sel:DWORD dst_unused:UNUSED_PAD src0_sel:WORD_1 src1_sel:DWORD
	v_add3_u32 v70, v174, v5, s9
	v_add3_u32 v5, v177, v6, s9
	v_add3_u32 v6, v175, v7, s9
	v_add3_u32 v7, v180, v20, s9
	v_add3_u32 v20, v181, v22, s9
	v_add3_u32 v22, v179, v23, s9
	v_add3_u32 v4, v176, v4, s9
	v_add3_u32 v21, v178, v21, s9
	v_and_b32_e32 v5, 0xffff0000, v5
	v_and_b32_e32 v6, 0xffff0000, v6
	v_and_b32_e32 v20, 0xffff0000, v20
	v_and_b32_e32 v22, 0xffff0000, v22
	v_or_b32_sdwa v5, v5, v4 dst_sel:DWORD dst_unused:UNUSED_PAD src0_sel:DWORD src1_sel:WORD_1
	v_or_b32_sdwa v4, v6, v70 dst_sel:DWORD dst_unused:UNUSED_PAD src0_sel:DWORD src1_sel:WORD_1
	v_or_b32_sdwa v7, v20, v7 dst_sel:DWORD dst_unused:UNUSED_PAD src0_sel:DWORD src1_sel:WORD_1
	v_or_b32_sdwa v6, v22, v21 dst_sel:DWORD dst_unused:UNUSED_PAD src0_sel:DWORD src1_sel:WORD_1
	global_store_dwordx4 v[50:51], v[4:7], off offset:-2048
	v_mov_b32_e32 v70, v141
	v_mov_b32_e32 v71, v145
	v_mov_b32_e32 v75, v146
	v_pk_mul_f32 v[70:71], v[70:71], v[70:71]
	v_mov_b32_e32 v18, v177
	v_pk_fma_f32 v[54:55], v[54:55], v[54:55], v[70:71]
	v_pk_fma_f32 v[70:71], v[74:75], v[74:75], v[72:73]
	v_mov_b32_e32 v19, v181
	v_pk_add_f32 v[54:55], v[54:55], v[70:71]
	v_mov_b32_e32 v70, v151
	v_add_f32_e32 v54, v54, v55
	v_mov_b32_e32 v71, v155
	v_add_f32_e32 v69, v69, v54
	v_mov_b32_e32 v54, v150
	v_mov_b32_e32 v55, v154
	v_pk_mul_f32 v[70:71], v[70:71], v[70:71]
	v_mov_b32_e32 v16, v176
	v_pk_fma_f32 v[10:11], v[54:55], v[54:55], v[70:71]
	v_mov_b32_e32 v17, v180
	v_pk_add_f32 v[8:9], v[8:9], v[10:11]
	v_pk_mul_f32 v[18:19], v[18:19], v[18:19]
	v_add_f32_e32 v8, v8, v9
	v_add_f32_e32 v69, v69, v8
	s_waitcnt lgkmcnt(2)
	v_mfma_f32_16x16x32_bf16 v[0:3], v[4:7], v[24:27], v[0:3]
	s_waitcnt vmcnt(9)
	v_and_b32_sdwa v9, v182, v67 dst_sel:DWORD dst_unused:UNUSED_PAD src0_sel:WORD_1 src1_sel:DWORD
	v_and_b32_sdwa v10, v185, v67 dst_sel:DWORD dst_unused:UNUSED_PAD src0_sel:WORD_1 src1_sel:DWORD
	v_and_b32_sdwa v11, v183, v67 dst_sel:DWORD dst_unused:UNUSED_PAD src0_sel:WORD_1 src1_sel:DWORD
	s_waitcnt vmcnt(8)
	v_and_b32_sdwa v54, v188, v67 dst_sel:DWORD dst_unused:UNUSED_PAD src0_sel:WORD_1 src1_sel:DWORD
	v_and_b32_sdwa v70, v189, v67 dst_sel:DWORD dst_unused:UNUSED_PAD src0_sel:WORD_1 src1_sel:DWORD
	v_and_b32_sdwa v71, v187, v67 dst_sel:DWORD dst_unused:UNUSED_PAD src0_sel:WORD_1 src1_sel:DWORD
	v_and_b32_sdwa v8, v184, v67 dst_sel:DWORD dst_unused:UNUSED_PAD src0_sel:WORD_1 src1_sel:DWORD
	v_and_b32_sdwa v55, v186, v67 dst_sel:DWORD dst_unused:UNUSED_PAD src0_sel:WORD_1 src1_sel:DWORD
	v_add3_u32 v72, v182, v9, s9
	v_add3_u32 v9, v185, v10, s9
	v_add3_u32 v10, v183, v11, s9
	v_add3_u32 v11, v188, v54, s9
	v_add3_u32 v54, v189, v70, s9
	v_add3_u32 v70, v187, v71, s9
	v_add3_u32 v8, v184, v8, s9
	v_add3_u32 v55, v186, v55, s9
	v_and_b32_e32 v9, 0xffff0000, v9
	v_and_b32_e32 v10, 0xffff0000, v10
	v_and_b32_e32 v54, 0xffff0000, v54
	v_and_b32_e32 v70, 0xffff0000, v70
	v_or_b32_sdwa v9, v9, v8 dst_sel:DWORD dst_unused:UNUSED_PAD src0_sel:DWORD src1_sel:WORD_1
	v_or_b32_sdwa v8, v10, v72 dst_sel:DWORD dst_unused:UNUSED_PAD src0_sel:DWORD src1_sel:WORD_1
	v_or_b32_sdwa v11, v54, v11 dst_sel:DWORD dst_unused:UNUSED_PAD src0_sel:DWORD src1_sel:WORD_1
	v_or_b32_sdwa v10, v70, v55 dst_sel:DWORD dst_unused:UNUSED_PAD src0_sel:DWORD src1_sel:WORD_1
	global_store_dwordx4 v[50:51], v[8:11], off offset:-1024
	v_mov_b32_e32 v54, v159
	v_mov_b32_e32 v55, v173
	v_mov_b32_e32 v52, v158
	v_mov_b32_e32 v53, v172
	v_pk_mul_f32 v[54:55], v[54:55], v[54:55]
	v_mov_b32_e32 v6, v183
	v_pk_fma_f32 v[14:15], v[52:53], v[52:53], v[54:55]
	v_mov_b32_e32 v7, v187
	v_pk_add_f32 v[12:13], v[12:13], v[14:15]
	v_mov_b32_e32 v14, v175
	v_add_f32_e32 v12, v12, v13
	v_mov_b32_e32 v15, v179
	v_add_f32_e32 v52, v69, v12
	v_mov_b32_e32 v12, v174
	v_mov_b32_e32 v13, v178
	v_pk_mul_f32 v[14:15], v[14:15], v[14:15]
	v_mov_b32_e32 v4, v182
	v_pk_fma_f32 v[12:13], v[12:13], v[12:13], v[14:15]
	v_pk_fma_f32 v[14:15], v[16:17], v[16:17], v[18:19]
	v_mov_b32_e32 v5, v186
	v_pk_add_f32 v[12:13], v[12:13], v[14:15]
	v_mov_b32_e32 v14, v185
	v_add_f32_e32 v12, v12, v13
	v_mov_b32_e32 v15, v189
	v_add_f32_e32 v16, v52, v12
	v_mov_b32_e32 v12, v184
	v_mov_b32_e32 v13, v188
	v_pk_mul_f32 v[6:7], v[6:7], v[6:7]
	v_pk_mul_f32 v[14:15], v[14:15], v[14:15]
	v_pk_fma_f32 v[4:5], v[4:5], v[4:5], v[6:7]
	v_pk_fma_f32 v[6:7], v[12:13], v[12:13], v[14:15]
	s_waitcnt lgkmcnt(1)
	v_mfma_f32_16x16x32_bf16 v[0:3], v[8:11], v[28:31], v[0:3]
	v_add_f32_e64 v4, v4, v6
	v_add_f32_e64 v5, v5, v7
	s_waitcnt vmcnt(8)
	v_mov_b32_e32 v6, v193
	v_add_f32_e32 v4, v4, v5
	s_waitcnt vmcnt(7)
	v_mov_b32_e32 v7, v197
	v_and_b32_sdwa v19, v193, v67 dst_sel:DWORD dst_unused:UNUSED_PAD src0_sel:WORD_1 src1_sel:DWORD
	v_and_b32_sdwa v20, v191, v67 dst_sel:DWORD dst_unused:UNUSED_PAD src0_sel:WORD_1 src1_sel:DWORD
	v_and_b32_sdwa v23, v197, v67 dst_sel:DWORD dst_unused:UNUSED_PAD src0_sel:WORD_1 src1_sel:DWORD
	v_and_b32_sdwa v24, v195, v67 dst_sel:DWORD dst_unused:UNUSED_PAD src0_sel:WORD_1 src1_sel:DWORD
	v_add_f32_e32 v16, v16, v4
	v_mov_b32_e32 v4, v191
	v_mov_b32_e32 v5, v195
	v_and_b32_sdwa v17, v192, v67 dst_sel:DWORD dst_unused:UNUSED_PAD src0_sel:WORD_1 src1_sel:DWORD
	v_and_b32_sdwa v18, v190, v67 dst_sel:DWORD dst_unused:UNUSED_PAD src0_sel:WORD_1 src1_sel:DWORD
	v_and_b32_sdwa v21, v196, v67 dst_sel:DWORD dst_unused:UNUSED_PAD src0_sel:WORD_1 src1_sel:DWORD
	v_and_b32_sdwa v22, v194, v67 dst_sel:DWORD dst_unused:UNUSED_PAD src0_sel:WORD_1 src1_sel:DWORD
	v_pk_mul_f32 v[14:15], v[6:7], v[6:7]
	v_add3_u32 v6, v193, v19, s9
	v_add3_u32 v7, v191, v20, s9
	v_add3_u32 v19, v197, v23, s9
	v_add3_u32 v20, v195, v24, s9
	v_pk_mul_f32 v[12:13], v[4:5], v[4:5]
	v_add3_u32 v4, v190, v18, s9
	v_add3_u32 v5, v192, v17, s9
	v_add3_u32 v17, v194, v22, s9
	v_add3_u32 v18, v196, v21, s9
	v_and_b32_e32 v6, 0xffff0000, v6
	v_and_b32_e32 v7, 0xffff0000, v7
	v_and_b32_e32 v19, 0xffff0000, v19
	v_and_b32_e32 v20, 0xffff0000, v20
	v_or_b32_sdwa v5, v6, v5 dst_sel:DWORD dst_unused:UNUSED_PAD src0_sel:DWORD src1_sel:WORD_1
	v_or_b32_sdwa v4, v7, v4 dst_sel:DWORD dst_unused:UNUSED_PAD src0_sel:DWORD src1_sel:WORD_1
	v_or_b32_sdwa v7, v19, v18 dst_sel:DWORD dst_unused:UNUSED_PAD src0_sel:DWORD src1_sel:WORD_1
	v_or_b32_sdwa v6, v20, v17 dst_sel:DWORD dst_unused:UNUSED_PAD src0_sel:DWORD src1_sel:WORD_1
	v_mov_b32_e32 v8, v190
	v_mov_b32_e32 v9, v194
	v_mov_b32_e32 v10, v192
	v_mov_b32_e32 v11, v196
	v_pk_fma_f32 v[8:9], v[8:9], v[8:9], v[12:13]
	v_pk_fma_f32 v[10:11], v[10:11], v[10:11], v[14:15]
	s_waitcnt lgkmcnt(0)
	v_mfma_f32_16x16x32_bf16 v[0:3], v[4:7], v[32:35], v[0:3]
	v_add_f32_e64 v8, v8, v10
	v_add_f32_e64 v9, v9, v11
	global_store_dwordx4 v[50:51], v[4:7], off
	v_add_f32_e32 v8, v8, v9
	v_lshl_add_u64 v[50:51], v[50:51], 0, s[16:17]
	v_add_f32_e32 v69, v16, v8
	s_cbranch_scc0 .LBB0_114
	ds_bpermute_b32 v4, v57, v69
	s_andn2_b64 vcc, exec, s[12:13]
	s_waitcnt lgkmcnt(0)
	v_add_f32_e32 v4, v69, v4
	ds_bpermute_b32 v5, v58, v4
	s_waitcnt lgkmcnt(0)
	v_add_f32_e32 v8, v4, v5
	s_cbranch_vccnz .LBB0_119
	ds_write_b128 v59, v[0:3]
	s_and_saveexec_b64 s[4:5], s[2:3]
	v_add_u32_e32 v4, v59, v60
	ds_write_b32 v4, v8 offset:1024
	s_or_b64 exec, exec, s[4:5]
